# adds: GLA scan producers issue all 8 gate-logit LDS reads up front (counted lgkmcnt) and all 8 score-operand LDS reads before the 4 MFMAs
# speedup vs baseline: 1.0025x; 1.0025x over previous
; __device__ __forceinline__ void gla_scan_phase2(LAS unsigned char* lds, const bf16_t* proj, const float* gbuf, const float* wgu  , const float* bg  ,
;                                                 bf16_t* ob0, bf16_t* ob1) {
;     ...
;                 if (n < NCH) {
;                     const int tok0 = b * SEQ + (dir ? NCH - 1 - n : n) * CH;
;                     LAS unsigned char* set = lds + (n & 1) * G2_SET;
;                     const f32x4 ga = gna, gb = gnb;
;                     const unsigned srow = (unsigned)tok0 * (unsigned)(GINP * 2);
;     ...
;                         unsigned c0[8], c1[8];
; #pragma unroll
;                         for (int t = 0; t < 8; ++t) { const unsigned a_ = vw[2 * t], b_ = vw[2 * t + 1]; c0[t] = (a_ & 0xffffu) | (b_ << 16); c1[t] = (a_ >> 16) | (b_ & 0xffff0000u); }
;                         *(LAS u32x4*)(set + G2_VT + (2 * d) * 80 + seg * 32) = (u32x4){c0[0], c0[1], c0[2], c0[3]};
;                         *(LAS u32x4*)(set + G2_VT + (2 * d) * 80 + seg * 32 + 16) = (u32x4){c0[4], c0[5], c0[6], c0[7]};
;                         *(LAS u32x4*)(set + G2_VT + (2 * d + 1) * 80 + seg * 32) = (u32x4){c1[0], c1[1], c1[2], c1[3]};
;                         *(LAS u32x4*)(set + G2_VT + (2 * d + 1) * 80 + seg * 32 + 16) = (u32x4){c1[4], c1[5], c1[6], c1[7]};
;                     }
;                     G2_BAR();
;                     {
;                         const int ti = wave >> 1, tj = wave & 1;
;                         f32x4 a4 = (f32x4){0.f, 0.f, 0.f, 0.f};
; #pragma unroll
;                         for (int ks = 0; ks < 4; ++ks) {
;                             const bf16x8 ka = *(const LAS bf16x8*)(lds + G2_KI + (16 * tj + fr) * 272 + ks * 64 + fq * 16);
;                             const bf16x8 qb = *(const LAS bf16x8*)(set + G2_QD + (16 * ti + fr) * 272 + ks * 64 + fq * 16);
;                             a4 = MFMA16(ka, qb, a4);
;                         }
;                         const int qi = 16 * ti + fr, kj = 16 * tj + 4 * fq;
;                         float m[4];
; #pragma unroll
;                         for (int e = 0; e < 4; ++e) { const bool keep = dir ? (kj + e > qi) : (kj + e <= qi); m[e] = keep ? a4[e] : 0.f; }
;                         u32x2 w; w.x = pk2(m[0], m[1]); w.y = pk2(m[2], m[3]);
;                         *(LAS u32x2*)(set + G2_SC + qi * 80 + kj * 2) = w;
;                     }
.LBB0_219:
	s_or_b64 exec, exec, s[6:7]
	s_waitcnt vmcnt(17)
	v_lshrrev_b32_e32 v17, 16, v68
	s_waitcnt vmcnt(15)
	v_lshrrev_b32_e32 v18, 16, v66
	s_waitcnt vmcnt(13)
	v_lshrrev_b32_e32 v19, 16, v64
	v_and_b32_e32 v16, 0xffff, v68
	v_and_or_b32 v20, v69, s77, v17
	v_and_b32_e32 v17, 0xffff, v66
	v_and_or_b32 v21, v67, s77, v18
	v_and_b32_e32 v18, 0xffff, v64
	s_waitcnt vmcnt(12)
	v_and_or_b32 v22, v65, s77, v19
	s_waitcnt vmcnt(11)
	v_and_b32_e32 v19, 0xffff, v62
	s_waitcnt vmcnt(9)
	v_lshrrev_b32_e32 v25, 16, v60
	s_waitcnt vmcnt(7)
	v_lshrrev_b32_e32 v26, 16, v58
	s_waitcnt vmcnt(5)
	v_lshrrev_b32_e32 v27, 16, v56
	v_lshl_or_b32 v16, v69, 16, v16
	v_lshl_or_b32 v17, v67, 16, v17
	v_lshl_or_b32 v18, v65, 16, v18
	v_lshl_or_b32 v19, v63, 16, v19
	v_lshrrev_b32_e32 v23, 16, v62
	v_and_b32_e32 v24, 0xffff, v60
	v_and_or_b32 v28, v61, s77, v25
	v_and_b32_e32 v25, 0xffff, v58
	v_and_or_b32 v29, v59, s77, v26
	v_and_b32_e32 v26, 0xffff, v56
	s_waitcnt vmcnt(4)
	v_and_or_b32 v30, v57, s77, v27
	s_waitcnt vmcnt(3)
	v_and_b32_e32 v27, 0xffff, v54
	v_lshrrev_b32_e32 v31, 16, v54
	v_add3_u32 v54, s15, v205, v204
	v_and_or_b32 v23, v63, s77, v23
	v_lshl_or_b32 v24, v61, 16, v24
	v_lshl_or_b32 v25, v59, 16, v25
	v_lshl_or_b32 v26, v57, 16, v26
	s_waitcnt vmcnt(2)
	v_lshl_or_b32 v27, v55, 16, v27
	v_and_or_b32 v31, v55, s77, v31
	ds_write_b128 v54, v[16:19] offset:18944
	ds_write_b128 v54, v[24:27] offset:18960
	ds_write_b128 v54, v[20:23] offset:19024
	ds_write_b128 v54, v[28:31] offset:19040
	s_waitcnt lgkmcnt(0)
	s_barrier
	v_add3_u32 v28, s15, v207, v206
	ds_read_b128 v[134:137], v233
	ds_read_b128 v[138:141], v28
	ds_read_b128 v[142:145], v233 offset:64
	ds_read_b128 v[146:149], v28 offset:64
	ds_read_b128 v[150:153], v233 offset:128
	ds_read_b128 v[154:157], v28 offset:128
	ds_read_b128 v[162:165], v233 offset:192
	ds_read_b128 v[166:169], v28 offset:192
	s_add_i32 s20, s20, 1
	s_add_i32 s8, s8, -1
	s_waitcnt lgkmcnt(6)
	v_mfma_f32_16x16x32_bf16 v[16:19], v[134:137], v[138:141], 0
	s_waitcnt lgkmcnt(4)
	v_mfma_f32_16x16x32_bf16 v[16:19], v[142:145], v[146:149], v[16:19]
	s_waitcnt lgkmcnt(2)
	v_mfma_f32_16x16x32_bf16 v[16:19], v[150:153], v[154:157], v[16:19]
	s_cmp_eq_u32 s20, 64
	s_waitcnt lgkmcnt(0)
	v_mfma_f32_16x16x32_bf16 v[16:19], v[162:165], v[166:169], v[16:19]
	s_nop 7
	v_cndmask_b32_e64 v16, 0, v16, s[50:51]
	v_cndmask_b32_e64 v17, 0, v17, s[52:53]
	v_cndmask_b32_e64 v18, 0, v18, s[54:55]
	v_cndmask_b32_e64 v19, 0, v19, s[56:57]
	v_cvt_pk_bf16_f32 v16, v16, v17
	v_cvt_pk_bf16_f32 v17, v18, v19
	v_add3_u32 v18, s15, v208, v209
	ds_write_b64 v18, v[16:17] offset:39424
	s_waitcnt lgkmcnt(0)
	s_barrier
	s_cbranch_scc1 .LBB0_211
.LBB0_220:
	s_waitcnt vmcnt(0)
	v_cvt_pk_bf16_f32 v102, v44, v45
	v_lshlrev_b32_e32 v16, 16, v102
	v_and_b32_e32 v17, 0xffff0000, v102
	v_cvt_pk_bf16_f32 v103, v46, v47
	v_cvt_pk_bf16_f32 v104, v40, v41
	v_cvt_pk_bf16_f32 v105, v42, v43
	v_pk_add_f32 v[16:17], v[44:45], v[16:17] neg_lo:[0,1] neg_hi:[0,1]
	s_and_b64 s[6:7], s[48:49], exec
	v_cvt_pk_bf16_f32 v44, v16, v17
	v_lshlrev_b32_e32 v16, 16, v103
	v_and_b32_e32 v17, 0xffff0000, v103
	v_pk_add_f32 v[16:17], v[46:47], v[16:17] neg_lo:[0,1] neg_hi:[0,1]
	s_cselect_b32 s0, s20, s8
	v_cvt_pk_bf16_f32 v45, v16, v17
	v_lshlrev_b32_e32 v16, 16, v104
	v_and_b32_e32 v17, 0xffff0000, v104
	v_pk_add_f32 v[16:17], v[40:41], v[16:17] neg_lo:[0,1] neg_hi:[0,1]
	v_lshlrev_b32_e32 v40, 16, v105
	v_cvt_pk_bf16_f32 v46, v16, v17
	v_mfma_f32_32x32x16_bf16 v[16:31], v[102:105], v[32:35], v[0:15]
	v_and_b32_e32 v41, 0xffff0000, v105
	v_add_f32_e64 v40, v42, -v40
	v_add_f32_e64 v41, v43, -v41
	s_lshl_b32 s0, s0, 5
	v_cvt_pk_bf16_f32 v47, v40, v41
	s_add_i32 s0, s0, s9
	s_mulk_i32 s0, 0x1a00
	s_or_b32 s6, s0, 0x1a00
	v_mfma_f32_32x32x16_bf16 v[16:31], v[44:47], v[32:35], v[16:31]
	s_or_b32 s7, s0, 0x3400
	s_add_i32 s15, s0, 0x4e00
	s_add_i32 s21, s0, 0x6800
	s_add_i32 s24, s0, 0x8200
	s_add_i32 s25, s0, 0x9c00
	s_add_i32 s26, s0, 0xb600
	s_add_i32 s28, s0, 0xd000
	s_add_i32 s33, s0, 0xea00
	s_add_i32 s78, s0, 0x10400
	s_add_i32 s79, s0, 0x11e00
	s_add_i32 s80, s0, 0x13800
	s_add_i32 s81, s0, 0x15200
	s_add_i32 s82, s0, 0x16c00
	s_add_i32 s83, s0, 0x18600
	s_cmp_lt_u32 s20, 63
	buffer_load_ushort v98, v50, s[64:67], s0 offen
	buffer_load_ushort v100, v50, s[64:67], s6 offen
	buffer_load_ushort v94, v50, s[64:67], s7 offen
	buffer_load_ushort v96, v50, s[64:67], s15 offen
	buffer_load_ushort v90, v50, s[64:67], s21 offen
	buffer_load_ushort v92, v50, s[64:67], s24 offen
	buffer_load_ushort v82, v50, s[64:67], s25 offen
	buffer_load_ushort v84, v50, s[64:67], s26 offen
	buffer_load_ushort v99, v53, s[64:67], s0 offen
	buffer_load_ushort v101, v53, s[64:67], s6 offen
	buffer_load_ushort v95, v53, s[64:67], s7 offen
	buffer_load_ushort v97, v53, s[64:67], s15 offen
	buffer_load_ushort v91, v53, s[64:67], s21 offen
	buffer_load_ushort v93, v53, s[64:67], s24 offen
	buffer_load_ushort v83, v53, s[64:67], s25 offen
	buffer_load_ushort v85, v53, s[64:67], s26 offen
	buffer_load_ushort v86, v50, s[64:67], s28 offen
	buffer_load_ushort v88, v50, s[64:67], s33 offen
	buffer_load_ushort v78, v50, s[64:67], s78 offen
	buffer_load_ushort v80, v50, s[64:67], s79 offen
	buffer_load_ushort v74, v50, s[64:67], s80 offen
	buffer_load_ushort v76, v50, s[64:67], s81 offen
	buffer_load_ushort v70, v50, s[64:67], s82 offen
	buffer_load_ushort v72, v50, s[64:67], s83 offen
	buffer_load_ushort v87, v53, s[64:67], s28 offen
	buffer_load_ushort v89, v53, s[64:67], s33 offen
	buffer_load_ushort v79, v53, s[64:67], s78 offen
	buffer_load_ushort v81, v53, s[64:67], s79 offen
	buffer_load_ushort v75, v53, s[64:67], s80 offen
; #define LAS __attribute__((address_space(3)))
; __device__ __forceinline__ unsigned pk2(float lo, float hi) { f32x2 v = {lo, hi}; bf16x2_t b = __builtin_convertvector(v, bf16x2_t); return __builtin_bit_cast(unsigned, b); }
; __device__ __forceinline__ float bflo(unsigned w) { return __uint_as_float(w << 16); }
; __device__ __forceinline__ void gla_scan_phase2(LAS unsigned char* lds, const bf16_t* proj, const float* gbuf, const float* wgu  , const float* bg  ,
;                                                 bf16_t* ob0, bf16_t* ob1) {
;     ...
;                     for (int ii = 0; ii < 16; ++ii) { qv[ii] = __builtin_amdgcn_raw_buffer_load_b16(prs, qvoff, srow + (unsigned)(ii * GINP * 2), 0);
;                                                        kv[ii] = __builtin_amdgcn_raw_buffer_load_b16(prs, qvoff + 1024u, srow + (unsigned)(ii * GINP * 2), 0); }
;                     unsigned vw[16];
; #pragma unroll
;                     for (int ii = 0; ii < 16; ++ii) vw[ii] = __builtin_amdgcn_raw_buffer_load_b32(prs, vvoff, srow + (unsigned)(ii * GINP * 2), 0);
;                     { const int n1 = n + 1 < NCH ? n + 1 : n; const float* grow = gbuf + (size_t)(b * SEQ + (dir ? NCH - 1 - n1 : n1) * CH + r) * 32 + dir * 16 + 8 * hh;
;                       gna = *(const f32x4*)grow; gnb = *(const f32x4*)(grow + 4); }
;                     {
;                         u32x4 ah, al;
;                         ah.x = pk2(ga[0], ga[1]); ah.y = pk2(ga[2], ga[3]); ah.z = pk2(gb[0], gb[1]); ah.w = pk2(gb[2], gb[3]);
;                         al.x = pk2(ga[0] - bflo(ah.x), ga[1] - bfhi(ah.x)); al.y = pk2(ga[2] - bflo(ah.y), ga[3] - bfhi(ah.y));
;                         al.z = pk2(gb[0] - bflo(ah.z), gb[1] - bfhi(ah.z)); al.w = pk2(gb[2] - bflo(ah.w), gb[3] - bfhi(ah.w));
;                         const bf16x8 gah = __builtin_bit_cast(bf16x8, ah), gal = __builtin_bit_cast(bf16x8, al);
;                         f32x16 zacc;
; #pragma unroll
;                         for (int i = 0; i < 16; ++i) zacc[i] = zbias;
;                         zacc = MFMA32(gah, wbh, zacc); zacc = MFMA32(gal, wbh, zacc); zacc = MFMA32(gah, wbl, zacc);
; #pragma unroll
;                         for (int i = 0; i < 16; ++i) *(LAS float*)(lds + G2_Z + (((i & 3) + 8 * (i >> 2) + 4 * hh) * 128 + 32 * zd + r) * 4) = zacc[i];
;                     }
;                     G2_BAR();
	buffer_load_ushort v77, v53, s[64:67], s81 offen
	buffer_load_ushort v71, v53, s[64:67], s82 offen
	buffer_load_ushort v73, v53, s[64:67], s83 offen
	buffer_load_dword v68, v51, s[64:67], s0 offen
	buffer_load_dword v69, v51, s[64:67], s6 offen
	buffer_load_dword v66, v51, s[64:67], s7 offen
	buffer_load_dword v67, v51, s[64:67], s15 offen
	buffer_load_dword v64, v51, s[64:67], s21 offen
	buffer_load_dword v65, v51, s[64:67], s24 offen
	buffer_load_dword v62, v51, s[64:67], s25 offen
	buffer_load_dword v63, v51, s[64:67], s26 offen
	buffer_load_dword v60, v51, s[64:67], s28 offen
	buffer_load_dword v61, v51, s[64:67], s33 offen
	buffer_load_dword v58, v51, s[64:67], s78 offen
	buffer_load_dword v59, v51, s[64:67], s79 offen
	buffer_load_dword v56, v51, s[64:67], s80 offen
	buffer_load_dword v57, v51, s[64:67], s81 offen
	buffer_load_dword v54, v51, s[64:67], s82 offen
	buffer_load_dword v55, v51, s[64:67], s83 offen
	s_cselect_b64 s[6:7], -1, 0
	s_cmp_lg_u64 s[6:7], 0
	s_addc_u32 s0, s20, 0
	s_cmp_lg_u64 s[6:7], 0
	s_subb_u32 s6, 0, 0
	v_mfma_f32_32x32x16_bf16 v[16:31], v[102:105], v[36:39], v[16:31]
	s_add_i32 s15, s8, s6
	s_and_b64 s[6:7], s[48:49], exec
	s_cselect_b32 s0, s0, s15
	v_lshl_add_u32 v40, s0, 5, v52
	v_ashrrev_i32_e32 v41, 31, v40
	v_lshlrev_b64 v[40:41], 7, v[40:41]
	v_lshl_add_u64 v[44:45], v[48:49], 0, v[40:41]
	global_load_dwordx4 v[40:43], v[44:45], off offset:16
	s_nop 0
	global_load_dwordx4 v[44:47], v[44:45], off
	s_nop 1
	ds_write_b32 v214, v16
	ds_write_b32 v215, v17
	ds_write_b32 v216, v18
	ds_write_b32 v217, v19
	ds_write_b32 v218, v20
	ds_write_b32 v219, v21
	ds_write_b32 v220, v22
	ds_write_b32 v221, v23
	ds_write_b32 v222, v24
	ds_write_b32 v223, v25
	ds_write_b32 v224, v26
	ds_write_b32 v225, v27
	ds_write_b32 v226, v28
	ds_write_b32 v227, v29
	ds_write_b32 v228, v30
	ds_write_b32 v229, v31
	s_waitcnt lgkmcnt(0)
	s_barrier
; #define LAS __attribute__((address_space(3)))
; __device__ __forceinline__ void gla_scan_phase2(LAS unsigned char* lds, const bf16_t* proj, const float* gbuf, const float* wgu  , const float* bg  ,
;                                                 bf16_t* ob0, bf16_t* ob1) {
;     ...
;                     float cs[16];
; #pragma unroll
;                     for (int ii = 0; ii < 16; ++ii) {
;                         const float z = *(const LAS float*)(lds + G2_Z + ((16 * seg + ii) * 128 + d) * 4);
;                         cs[ii] = fminf(z, 0.f) * (1.4426950408889634f / 16.f) - __builtin_amdgcn_logf(1.f + __builtin_amdgcn_exp2f(fabsf(z) * -1.4426950408889634f)) * (1.f / 16.f);
;                     }
;                     if (dir == 0) {
; #pragma unroll
;                         for (int ii = 1; ii < 16; ++ii) cs[ii] += cs[ii - 1];
;                         *(LAS float*)(lds + G2_SEG + (seg * 128 + d) * 4) = cs[15];
;                     } else {
; #pragma unroll
;     ...
;                         *(LAS float*)(lds + G2_SEG + (seg * 128 + d) * 4) = cs[0];
;                     }
	ds_read2st64_b32 v[118:119], v230 offset1:2
	ds_read2st64_b32 v[120:121], v230 offset0:4 offset1:6
	ds_read2st64_b32 v[122:123], v230 offset0:8 offset1:10
	ds_read2st64_b32 v[124:125], v230 offset0:12 offset1:14
	ds_read2st64_b32 v[126:127], v230 offset0:16 offset1:18
	ds_read2st64_b32 v[128:129], v230 offset0:20 offset1:22
	ds_read2st64_b32 v[130:131], v230 offset0:24 offset1:26
	ds_read2st64_b32 v[132:133], v230 offset0:28 offset1:30
	s_andn2_b64 vcc, exec, s[68:69]
	s_mov_b64 s[6:7], -1
	s_waitcnt lgkmcnt(7)
	v_mov_b32_e32 v16, v118
	v_mov_b32_e32 v17, v119
	v_mul_f32_e64 v18, |v16|, s1
	v_exp_f32_e32 v18, v18
	v_max_f32_e32 v16, v16, v16
	v_min_f32_e32 v16, 0, v16
	v_add_f32_e32 v18, 1.0, v18
	v_log_f32_e32 v18, v18
	s_nop 0
	v_mul_f32_e32 v20, 0x3d800000, v18
	v_mul_f32_e64 v18, |v17|, s1
	v_exp_f32_e32 v21, v18
	v_fma_f32 v16, v16, s10, -v20
	s_nop 0
	v_max_f32_e32 v17, v17, v17
	v_add_f32_e32 v20, 1.0, v21
	v_log_f32_e32 v20, v20
	v_min_f32_e32 v17, 0, v17
	s_waitcnt lgkmcnt(6)
	v_mov_b32_e32 v18, v120
	v_mov_b32_e32 v19, v121
	v_mul_f32_e64 v21, |v18|, s1
	v_exp_f32_e32 v21, v21
	v_mul_f32_e32 v20, 0x3d800000, v20
	v_fma_f32 v25, v17, s10, -v20
	v_mul_f32_e64 v20, |v19|, s1
	v_exp_f32_e32 v20, v20
	v_add_f32_e32 v17, 1.0, v21
	v_log_f32_e32 v17, v17
	v_max_f32_e32 v18, v18, v18
	v_add_f32_e32 v20, 1.0, v20
	v_log_f32_e32 v22, v20
	s_nop 0
	v_min_f32_e32 v18, 0, v18
	v_mul_f32_e32 v17, 0x3d800000, v17
	v_fma_f32 v26, v18, s10, -v17
	v_max_f32_e32 v17, v19, v19
	s_waitcnt lgkmcnt(5)
	v_mov_b32_e32 v20, v122
	v_mov_b32_e32 v21, v123
	v_mul_f32_e64 v19, |v20|, s1
	v_exp_f32_e32 v19, v19
	v_min_f32_e32 v17, 0, v17
	v_mul_f32_e32 v18, 0x3d800000, v22
	v_fma_f32 v29, v17, s10, -v18
	v_add_f32_e32 v18, 1.0, v19
	v_max_f32_e32 v17, v20, v20
	v_log_f32_e32 v20, v18
	v_mul_f32_e64 v18, |v21|, s1
	v_exp_f32_e32 v22, v18
	s_nop 0
	v_min_f32_e32 v17, 0, v17
	v_mul_f32_e32 v20, 0x3d800000, v20
	v_fma_f32 v30, v17, s10, -v20
	v_add_f32_e32 v17, 1.0, v22
	s_waitcnt lgkmcnt(4)
	v_mov_b32_e32 v18, v124
	v_mov_b32_e32 v19, v125
	v_mul_f32_e64 v20, |v18|, s1
	v_exp_f32_e32 v20, v20
	v_log_f32_e32 v17, v17
	v_max_f32_e32 v21, v21, v21
	v_min_f32_e32 v21, 0, v21
	v_add_f32_e32 v20, 1.0, v20
	v_log_f32_e32 v20, v20
	v_mul_f32_e32 v17, 0x3d800000, v17
	v_fma_f32 v102, v21, s10, -v17
	v_max_f32_e32 v17, v18, v18
	v_mul_f32_e32 v18, 0x3d800000, v20
	v_mul_f32_e64 v20, |v19|, s1
	v_exp_f32_e32 v22, v20
	v_min_f32_e32 v17, 0, v17
	v_fma_f32 v104, v17, s10, -v18
	s_nop 0
	v_add_f32_e32 v18, 1.0, v22
	v_log_f32_e32 v18, v18
	v_max_f32_e32 v17, v19, v19
	v_min_f32_e32 v17, 0, v17
	s_waitcnt lgkmcnt(3)
	v_mov_b32_e32 v20, v126
	v_mov_b32_e32 v21, v127
	v_mul_f32_e64 v19, |v20|, s1
	v_mul_f32_e32 v18, 0x3d800000, v18
	v_fma_f32 v105, v17, s10, -v18
	v_mul_f32_e64 v18, |v21|, s1
	v_exp_f32_e32 v19, v19
	v_exp_f32_e32 v18, v18
	v_add_f32_e32 v17, 1.0, v19
	v_max_f32_e32 v19, v20, v20
	v_add_f32_e32 v18, 1.0, v18
	v_log_f32_e32 v17, v17
	v_min_f32_e32 v20, 0, v19
	v_log_f32_e32 v22, v18
	s_nop 0
	v_mul_f32_e32 v17, 0x3d800000, v17
	v_fma_f32 v108, v20, s10, -v17
	v_max_f32_e32 v17, v21, v21
	v_min_f32_e32 v17, 0, v17
	s_waitcnt lgkmcnt(2)
	v_mov_b32_e32 v18, v128
	v_mov_b32_e32 v19, v129
	v_mul_f32_e64 v21, |v18|, s1
	v_exp_f32_e32 v21, v21
	v_mul_f32_e32 v20, 0x3d800000, v22
	v_fma_f32 v109, v17, s10, -v20
	v_max_f32_e32 v17, v18, v18
	v_add_f32_e32 v18, 1.0, v21
	v_mul_f32_e64 v20, |v19|, s1
	v_log_f32_e32 v18, v18
	v_exp_f32_e32 v22, v20
	s_nop 0
	v_min_f32_e32 v17, 0, v17
	v_mul_f32_e32 v18, 0x3d800000, v18
	v_fma_f32 v111, v17, s10, -v18
	v_add_f32_e32 v17, 1.0, v22
	s_waitcnt lgkmcnt(1)
	v_mov_b32_e32 v20, v130
	v_mov_b32_e32 v21, v131
	v_mul_f32_e64 v18, |v20|, s1
	v_exp_f32_e32 v18, v18
	v_log_f32_e32 v17, v17
	v_max_f32_e32 v19, v19, v19
	v_min_f32_e32 v19, 0, v19
	v_add_f32_e32 v18, 1.0, v18
	v_log_f32_e32 v18, v18
	v_mul_f32_e32 v17, 0x3d800000, v17
	v_fma_f32 v112, v19, s10, -v17
	v_max_f32_e32 v17, v20, v20
	v_mul_f32_e32 v20, 0x3d800000, v18
	v_mul_f32_e64 v18, |v21|, s1
	v_exp_f32_e32 v22, v18
	v_min_f32_e32 v17, 0, v17
	s_nop 0
	v_fma_f32 v113, v17, s10, -v20
	v_add_f32_e32 v20, 1.0, v22
	v_log_f32_e32 v20, v20
	v_max_f32_e32 v17, v21, v21
	s_waitcnt lgkmcnt(0)
	v_mov_b32_e32 v18, v132
	v_mov_b32_e32 v19, v133
	v_mul_f32_e64 v21, |v18|, s1
	v_exp_f32_e32 v21, v21
	v_min_f32_e32 v17, 0, v17
	v_mul_f32_e32 v20, 0x3d800000, v20
	v_fma_f32 v114, v17, s10, -v20
	v_mul_f32_e64 v20, |v19|, s1
	v_exp_f32_e32 v20, v20
	v_add_f32_e32 v17, 1.0, v21
	v_log_f32_e32 v17, v17
	v_max_f32_e32 v18, v18, v18
	v_add_f32_e32 v20, 1.0, v20
	v_log_f32_e32 v20, v20
	v_min_f32_e32 v18, 0, v18
	v_mul_f32_e32 v17, 0x3d800000, v17
	v_fma_f32 v116, v18, s10, -v17
	v_max_f32_e32 v17, v19, v19
	v_min_f32_e32 v17, 0, v17
	v_mul_f32_e32 v18, 0x3d800000, v20
	v_fma_f32 v17, v17, s10, -v18
	s_cbranch_vccnz .LBB0_222
	v_add_f32_e32 v18, v116, v17
	v_add_f32_e32 v19, v114, v18
	v_add_f32_e32 v20, v113, v19
	v_add_f32_e32 v21, v112, v20
	v_add_f32_e32 v22, v111, v21
	v_add_f32_e32 v23, v109, v22
	v_add_f32_e32 v24, v108, v23
	v_add_f32_e32 v27, v105, v24
	v_add_f32_e32 v28, v104, v27
	v_add_f32_e32 v31, v102, v28
	v_add_f32_e32 v103, v30, v31
	v_add_f32_e32 v106, v29, v103
	v_add_f32_e32 v107, v26, v106
	v_add_f32_e32 v110, v25, v107
	v_add_f32_e32 v115, v16, v110
	s_mov_b64 s[6:7], 0
